# v36 + up-proj GEMM tile order groups 4 row-tiles x 8 column-tiles per XCD round (was 2 x 16): less distinct operand data per K step per XCD
# baseline (speedup 1.0000x reference)
; #define PG8_STAGE(bufoff, gbase, voff) do { _Pragma("unroll") for (int _i = 0; _i < 2; ++_i) \
;         __builtin_amdgcn_global_load_lds((const unsigned*)((const char*)(gbase) + (voff)[_i]), (PG8_LAS unsigned*)(lds + (bufoff) + ldsw + _i * 8192), 16, 0, 0); } while (0)
; #define PG8_WAIT_V(n) asm volatile("s_waitcnt vmcnt(" #n ")" ::: "memory")
; #define PG8_BAR __builtin_amdgcn_s_barrier()
;     __host__ __device__ bool next(int i, Unit& u) const {
;         const long L = (long)i * G + c; if (L >= nwg) return false;
;         int wgid = (int)L; { const int q = nwg / NXCD, r = nwg % NXCD, xcd = wgid % NXCD, off = wgid / NXCD; wgid = (xcd < r ? xcd * (q + 1) : r * (q + 1) + (xcd - r) * q) + off; }
;         const int nig = wgm * nN, gid = wgid / nig, fm = gid * wgm, gsz = (nM - fm) < wgm ? (nM - fm) : wgm;
;         u.pm = fm + ((wgid % nig) % gsz); u.pn = (wgid % nig) / gsz; return true;
; template <class Epi, class Sched, bool ALIGN_EPI = false, bool SP2 = false>
; __device__ __forceinline__ void gemm_phase(PG8_LAS unsigned char* lds, const Gemm g, const Sched& S, const Epi& E) {
;     ...
;     const char* cA = (const char*)g.A + (size_t)cur.pm * tstep; const char* cB = (const char*)g.Bt + (size_t)cur.pn * tstep;
;     S.a_ready(cur);
;     if constexpr (SP2) {
;         PG8_STAGE(PG8_SB(0, 0), cB, voffB); PG8_STAGE(PG8_SB(0, 1), cB + hstep, voffB); PG8_STAGE(PG8_SA(0, 0), cA, voffA); PG8_STAGE(PG8_SA(0, 1), cA + hstep, voffA);
;         if (wr == 1) PG8_BAR;
;         PG8_WAIT_V(2); PG8_BAR;
.LBB0_616:
	v_lshrrev_b32_e32 v147, 2, v253
	v_and_b32_e32 v146, 15, v253
	s_cmpk_gt_i32 s92, 0x3ff
	v_readfirstlane_b32 s1, v253
	s_cbranch_scc1 .LBB0_636
	v_lshlrev_b32_e32 v2, 1, v147
	v_lshrrev_b32_e32 v3, 5, v253
	v_and_b32_e32 v2, 24, v2
	v_and_b32_e32 v3, 4, v3
	v_and_b32_e32 v4, 3, v147
	v_lshlrev_b32_e32 v0, 4, v253
	v_and_b32_e32 v1, 32, v253
	v_and_b32_e32 v10, 15, v147
	v_or3_b32 v2, v3, v4, v2
	v_lshrrev_b32_e32 v3, 3, v253
	s_movk_i32 s0, 0x70
	v_bitop3_b32 v8, v0, v1, 48 bitop3:0x6c
	v_and_b32_e32 v9, 64, v253
	v_and_or_b32 v4, v3, s0, v10
	s_movk_i32 s0, 0x60
	s_waitcnt lgkmcnt(0)
	v_add_u32_e32 v11, 0x2000, v0
	v_or_b32_e32 v1, v8, v9
	v_and_or_b32 v3, v3, s0, v2
	v_lshrrev_b32_e32 v0, 7, v11
	s_movk_i32 s0, 0xf0
	v_lshl_or_b32 v130, v3, 12, v1
	v_and_or_b32 v3, v0, s0, v10
	s_movk_i32 s0, 0xe0
	s_ashr_i32 s36, s92, 31
	v_and_or_b32 v0, v0, s0, v2
	s_lshr_b32 s0, s36, 29
	s_add_i32 s0, s92, s0
	s_ashr_i32 s2, s0, 3
	s_and_b32 s0, s0, -8
	s_lshr_b32 s8, s1, 6
	s_sub_i32 s0, s92, s0
	s_lshr_b32 s10, s1, 8
	s_lshl_b32 s33, s8, 10
	s_lshl_b32 s3, s0, 7
	s_cmp_lt_i32 s0, 0
	s_mulk_i32 s0, 0x81
	s_cselect_b32 s0, s0, s3
	s_add_i32 s0, s0, s2
	s_ashr_i32 s2, s0, 31
	s_lshr_b32 s2, s2, 25
	s_add_i32 s2, s0, s2
	s_ashr_i32 s3, s2, 7
	s_andn2_b32 s2, s2, 127
	s_sub_i32 s2, s0, s2
	s_lshr_b32 s0, s2, 2
	s_and_b32 s2, s2, 3
	s_lshl_b32 s3, s3, 2
	s_add_i32 s28, s3, s2
	s_ashr_i32 s29, s28, 31
	s_bfe_i64 s[2:3], s[0:1], 0x100000
	s_lshl_b64 s[6:7], s[28:29], 20
	s_lshl_b64 s[2:3], s[2:3], 20
	s_add_u32 s2, s86, s2
	s_addc_u32 s3, s87, s3
	s_add_i32 s29, s33, 0
	s_add_i32 m0, s29, 0x10000
	v_lshl_or_b32 v134, v0, 12, v1
	global_load_lds_dwordx4 v130, s[2:3]
	s_add_i32 m0, s29, 0x12000
	s_add_u32 s12, s2, 0x80000
	global_load_lds_dwordx4 v134, s[2:3]
	s_addc_u32 s13, s3, 0
	s_add_i32 m0, s29, 0x14000
	v_lshl_or_b32 v128, v4, 12, v1
	global_load_lds_dwordx4 v130, s[12:13]
	s_add_i32 m0, s29, 0x16000
	s_add_u32 s30, s66, s6
	s_addc_u32 s31, s67, s7
	s_add_i32 s37, s29, 0x2000
	global_load_lds_dwordx4 v134, s[12:13]
	s_mov_b32 m0, s29
	s_add_u32 s6, s30, 0x80000
	v_lshl_or_b32 v132, v3, 12, v1
	global_load_lds_dwordx4 v128, s[30:31]
	s_mov_b32 m0, s37
	s_addc_u32 s7, s31, 0
	s_add_i32 s38, s29, 0x4000
	global_load_lds_dwordx4 v132, s[30:31]
	s_mov_b32 m0, s38
	s_add_i32 s39, s29, 0x6000
	global_load_lds_dwordx4 v128, s[6:7]
	s_mov_b32 m0, s39
	v_mov_b32_e32 v131, 0
	global_load_lds_dwordx4 v132, s[6:7]
	v_mov_b32_e32 v135, v131
	v_mov_b32_e32 v129, v131
	v_mov_b32_e32 v133, v131
	s_cmp_eq_u32 s10, 1
	s_mov_b32 s40, 0
	v_lshl_add_u64 v[6:7], s[2:3], 0, v[130:131]
	v_lshl_add_u64 v[4:5], s[2:3], 0, v[134:135]
	v_lshl_add_u64 v[0:1], s[30:31], 0, v[128:129]
	s_cselect_b64 s[6:7], -1, 0
	s_cmp_lg_u32 s10, 1
	v_lshl_add_u64 v[2:3], s[30:31], 0, v[132:133]
	s_cbranch_scc1 .LBB0_619
	s_barrier

;     __host__ __device__ bool next(int i, Unit& u) const {
;         const long L = (long)i * G + c; if (L >= nwg) return false;
;         int wgid = (int)L; { const int q = nwg / NXCD, r = nwg % NXCD, xcd = wgid % NXCD, off = wgid / NXCD; wgid = (xcd < r ? xcd * (q + 1) : r * (q + 1) + (xcd - r) * q) + off; }
;         const int nig = wgm * nN, gid = wgid / nig, fm = gid * wgm, gsz = (nM - fm) < wgm ? (nM - fm) : wgm;
;         u.pm = fm + ((wgid % nig) % gsz); u.pn = (wgid % nig) / gsz; return true;
; template <class Epi, class Sched, bool ALIGN_EPI = false, bool SP2 = false>
; __device__ __forceinline__ void gemm_phase(PG8_LAS unsigned char* lds, const Gemm g, const Sched& S, const Epi& E) {
;     ...
;         const bool has_next = S.next(ui + 1, nxt);
;         const char* nA = has_next ? (const char*)g.A + (size_t)nxt.pm * tstep : cA; const char* nB = has_next ? (const char*)g.Bt + (size_t)nxt.pn * tstep : cB;
.LBB0_627:
	s_ashr_i32 s20, s22, 3
	s_add_i32 s20, s24, s20
	s_ashr_i32 s21, s20, 31
	s_lshr_b32 s21, s21, 25
	s_add_i32 s21, s20, s21
	s_ashr_i32 s22, s21, 7
	s_lshl_b32 s22, s22, 2
	s_sub_i32 s23, 32, s22
	s_min_i32 s23, s23, 4
	s_abs_i32 s24, s23
	v_cvt_f32_u32_e32 v0, s24
	s_sub_i32 s26, 0, s24
	s_andn2_b32 s21, s21, 127
	s_sub_i32 s21, s20, s21
	v_rcp_iflag_f32_e32 v0, v0
	s_abs_i32 s20, s21
	s_xor_b32 s25, s21, s23
	s_ashr_i32 s25, s25, 31
	v_mul_f32_e32 v0, 0x4f7ffffe, v0
	v_cvt_u32_f32_e32 v0, v0
	s_nop 0
	v_readfirstlane_b32 s27, v0
	s_mul_i32 s26, s26, s27
	s_mul_hi_u32 s26, s27, s26
	s_add_i32 s27, s27, s26
	s_mul_hi_u32 s26, s20, s27
	s_mul_i32 s27, s26, s24
	s_sub_i32 s20, s20, s27
	s_add_i32 s34, s26, 1
	s_sub_i32 s27, s20, s24
	s_cmp_ge_u32 s20, s24
	s_cselect_b32 s26, s34, s26
	s_cselect_b32 s20, s27, s20
	s_add_i32 s27, s26, 1
	s_cmp_ge_u32 s20, s24
	s_cselect_b32 s20, s27, s26
	s_xor_b32 s20, s20, s25
	s_sub_i32 s20, s20, s25
	s_mul_i32 s23, s20, s23
	s_sub_i32 s21, s21, s23
	s_add_i32 s22, s22, s21
